# in-proj / out-proj GEMM: next unit's tile coordinates by +4 column tiles with wrap (no per-unit integer-division emulation on eight waves)
# baseline (speedup 1.0000x reference)
;     __host__ __device__ bool next(int i, Unit& u) const { Unit m; if (!S.next(i >> 1, m)) return false; u.pm = m.pm; u.pn = m.pn + 4 * (i & 1); return true; }
;     __host__ __device__ bool next(int i, Unit& u) const { Unit m; if (!S.next(i >> 1, m)) return false; u.pm = m.pm + (i & 1) * dpm; u.pn = m.pn + (i & 1) * dpn; return true; }
;     __host__ __device__ bool next(int i, Unit& u) const {
;         const long L = (long)i * G + c; if (L >= nwg) return false;
;         int wgid = (int)L; { const int q = nwg / NXCD, r = nwg % NXCD, xcd = wgid % NXCD, off = wgid / NXCD; wgid = (xcd < r ? xcd * (q + 1) : r * (q + 1) + (xcd - r) * q) + off; }
;         const int nig = WGM * nN, gid = wgid / nig, fm = gid * WGM, gsz = (nM - fm) < WGM ? (nM - fm) : WGM;
;         u.pm = fm + ((wgid % nig) % gsz); u.pn = (wgid % nig) / gsz; return true;
;     }
; template <class Epi, class Sched, bool ALIGN_EPI = false, bool SP2 = false>
; __device__ __forceinline__ void gemm_phase(PG8_LAS unsigned char* lds, const Gemm g, const Sched& S, const Epi& E) {
;     ...
;         const bool has_next = S.next(ui + 1, nxt);
;         const char* nA = has_next ? (const char*)g.A + (size_t)nxt.pm * tstep : cA; const char* nB = has_next ? (const char*)g.Bt + (size_t)nxt.pn * tstep : cB;
.LBB0_150:
	s_add_i32 s81, s81, 1
	s_mul_i32 s4, s81, s33
	s_mul_hi_u32 s5, s81, s26
	s_add_i32 s5, s5, s4
	s_mul_i32 s4, s81, s26
	s_add_u32 s22, s4, s2
	s_addc_u32 s23, s5, s27
	v_cmp_ge_i64_e32 vcc, s[22:23], v[170:171]
	v_cmp_lt_i64_e64 s[4:5], s[22:23], v[170:171]
	s_cbranch_vccnz .LBB0_152
	s_add_i32 s18, s83, 4
	s_lshr_b32 s7, s47, 3
	s_sub_i32 s19, s18, s7
	s_add_i32 s21, s6, 8
	s_cmp_ge_u32 s18, s7
	s_cselect_b32 s18, s19, s18
	s_cselect_b32 s20, s21, s6

;     __host__ __device__ bool next(int i, Unit& u) const { Unit m; if (!S.next(i >> 1, m)) return false; u.pm = m.pm; u.pn = m.pn + 4 * (i & 1); return true; }
;     __host__ __device__ bool next(int i, Unit& u) const { Unit m; if (!S.next(i >> 1, m)) return false; u.pm = m.pm + (i & 1) * dpm; u.pn = m.pn + (i & 1) * dpn; return true; }
;     __host__ __device__ bool next(int i, Unit& u) const {
;         const long L = (long)i * G + c; if (L >= nwg) return false;
;         int wgid = (int)L; { const int q = nwg / NXCD, r = nwg % NXCD, xcd = wgid % NXCD, off = wgid / NXCD; wgid = (xcd < r ? xcd * (q + 1) : r * (q + 1) + (xcd - r) * q) + off; }
;         const int nig = WGM * nN, gid = wgid / nig, fm = gid * WGM, gsz = (nM - fm) < WGM ? (nM - fm) : WGM;
;         u.pm = fm + ((wgid % nig) % gsz); u.pn = (wgid % nig) / gsz; return true;
;     }
; template <class Epi, class Sched, bool ALIGN_EPI = false, bool SP2 = false>
; __device__ __forceinline__ void gemm_phase(PG8_LAS unsigned char* lds, const Gemm g, const Sched& S, const Epi& E) {
;     ...
;         const bool has_next = S.next(ui + 1, nxt);
;         const char* nA = has_next ? (const char*)g.A + (size_t)nxt.pm * tstep : cA; const char* nB = has_next ? (const char*)g.Bt + (size_t)nxt.pn * tstep : cB;
.LBB0_449:
	s_add_i32 s49, s49, 1
	s_mul_i32 s4, s49, s33
	s_mul_hi_u32 s5, s49, s26
	s_add_i32 s5, s5, s4
	s_mul_i32 s4, s49, s26
	s_add_u32 s16, s4, s2
	s_addc_u32 s17, s5, s27
	v_mov_b64_e32 v[0:1], 0x200
	v_cmp_lt_i64_e64 s[4:5], s[16:17], v[0:1]
	v_mov_b64_e32 v[0:1], 0x1ff
	v_cmp_gt_i64_e32 vcc, s[16:17], v[0:1]
	s_cbranch_vccnz .LBB0_455
	s_mov_b32 s12, s68
	s_add_i32 s14, s60, 8
